# speedup vs baseline: 1.0043x; 1.0043x over previous
; #define G_STAGE(bufoff, gbase, voff) do { _Pragma("unroll") for (int _i = 0; _i < 2; ++_i) \
;     __builtin_amdgcn_global_load_lds((const unsigned*)((const char*)(gbase) + (voff)[_i]), (LAS unsigned*)(lds + (bufoff) + ldsw + _i * 8192), 16, 0, 0); } while (0)
; #define G_LDA(dst, b, h) do { _Pragma("unroll") for (int m = 0; m < 4; ++m) _Pragma("unroll") for (int k = 0; k < 2; ++k) dst[m][k] = *(const LAS bf16x8*)(lds + G_SA(b, h) + aoff + m * 2048 + k * 1024); } while (0)
; #define G_LDB(dst, b, h) do { _Pragma("unroll") for (int n = 0; n < 2; ++n) _Pragma("unroll") for (int k = 0; k < 2; ++k) dst[n][k] = *(const LAS bf16x8*)(lds + G_SB(b, h) + boff + n * 2048 + k * 1024); } while (0)
; #define G_MMA(ai, bj, At, Bt) do { __builtin_amdgcn_s_setprio(1); _Pragma("unroll") for (int m = 0; m < 4; ++m) _Pragma("unroll") for (int n = 0; n < 2; ++n) _Pragma("unroll") for (int k = 0; k < 2; ++k) \
;     acc[ai][bj][m][n] = __builtin_amdgcn_mfma_f32_16x16x32_bf16(Bt[n][k], At[m][k], acc[ai][bj][m][n], 0, 0, 0); __builtin_amdgcn_s_setprio(0); } while (0)
; #define WAIT_V(n) asm volatile("s_waitcnt vmcnt(" #n ")" ::: "memory")
; #define WAIT_L(n) asm volatile("s_waitcnt lgkmcnt(" #n ")" ::: "memory")
; #define BAR __builtin_amdgcn_s_barrier()
; #define SCHED __builtin_amdgcn_sched_barrier(0)
; template <class Epi>
; __device__ __forceinline__ void gemm_phase(const bf16_t* __restrict__ A, int lda, const bf16_t* __restrict__ Bt, int ldb, int K, int nM, int nN, const Epi& epi, LAS unsigned char* lds, int wv) {
;     ...
;         for (int t = 0; t < nt; t += 2) {
;             const bool last = (t == nt - 2);
;             const char* a1 = cA + (size_t)(t + 1) * kstep;
;             const char* a2 = last ? nA : cA + (size_t)(t + 2) * kstep; const char* b2 = last ? nB : cB + (size_t)(t + 2) * kstep;
;             const char* a3 = a2 + kstep; const char* b3 = b2 + kstep;
;             G_LDB(B0, 0, 0); G_LDB(B1, 0, 1); SCHED; G_LDA(At, 0, 0); G_STAGE(G_SA(1, 1), a1 + hstep, voffA);
;             WAIT_V(8); WAIT_L(0); BAR; G_MMA(0, 0, At, B0); G_MMA(0, 1, At, B1); BAR; SCHED;
;             G_LDA(At, 0, 1); G_STAGE(G_SB(0, 0), b2, voffA); G_STAGE(G_SB(0, 1), b2 + hstep, voffA); G_STAGE(G_SA(0, 0), a2, voffA);
;             WAIT_V(8); WAIT_L(0); BAR; G_MMA(1, 0, At, B0); G_MMA(1, 1, At, B1); BAR; SCHED;
.LBB0_28:
	s_add_u32 s30, s83, s60
	s_addc_u32 s31, s94, s61
	s_add_u32 s30, s30, 0x2000100
	s_addc_u32 s31, s31, 0
	s_add_u32 s62, s81, s60
	s_addc_u32 s63, s82, s61
	s_add_i32 vcc_lo, 0, 0x10000
	s_cmpk_eq_i32 s60, 0x700
	s_cselect_b32 s69, s59, s31
	s_cselect_b32 s68, s51, s30
	s_cselect_b32 s63, s66, s63
	s_cselect_b32 s62, s53, s62
	s_add_i32 vcc_hi, 0, 0x14000
	v_add_u32_e32 v154, vcc_lo, v140
	v_add_u32_e32 v170, vcc_hi, v140
	ds_read_b128 v[142:145], v154
	ds_read_b128 v[146:149], v154 offset:1024
	ds_read_b128 v[150:153], v154 offset:2048
	ds_read_b128 v[154:157], v154 offset:3072
	ds_read_b128 v[158:161], v170
	ds_read_b128 v[162:165], v170 offset:1024
	ds_read_b128 v[166:169], v170 offset:2048
	ds_read_b128 v[170:173], v170 offset:3072
	v_lshl_add_u64 v[190:191], v[136:137], 0, s[60:61]
	s_add_i32 m0, s9, 0xc000
	ds_read_b128 v[174:177], v141
	ds_read_b128 v[178:181], v141 offset:1024
	ds_read_b128 v[182:185], v141 offset:2048
	ds_read_b128 v[186:189], v141 offset:3072
	ds_read_b128 v[194:197], v141 offset:4096
	ds_read_b128 v[198:201], v141 offset:5120
	ds_read_b128 v[202:205], v141 offset:6144
	ds_read_b128 v[206:209], v141 offset:7168
	global_load_lds_dwordx4 v[190:191], off
	v_lshl_add_u64 v[190:191], v[134:135], 0, s[60:61]
	s_add_i32 m0, s9, 0xe000
	s_nop 0
	global_load_lds_dwordx4 v[190:191], off
	s_waitcnt vmcnt(8)
	s_waitcnt lgkmcnt(0)
	s_barrier
	s_waitcnt lgkmcnt(0)
	v_mfma_f32_16x16x32_bf16 v[124:127], v[142:145], v[174:177], v[124:127]
	v_mfma_f32_16x16x32_bf16 v[120:123], v[150:153], v[174:177], v[120:123]
	v_mfma_f32_16x16x32_bf16 v[108:111], v[142:145], v[182:185], v[108:111]
	v_mfma_f32_16x16x32_bf16 v[104:107], v[150:153], v[182:185], v[104:107]
	v_mfma_f32_16x16x32_bf16 v[92:95], v[142:145], v[194:197], v[92:95]
	v_mfma_f32_16x16x32_bf16 v[88:91], v[150:153], v[194:197], v[88:91]
	v_mfma_f32_16x16x32_bf16 v[76:79], v[142:145], v[202:205], v[76:79]
	v_mfma_f32_16x16x32_bf16 v[72:75], v[150:153], v[202:205], v[72:75]
	v_mfma_f32_16x16x32_bf16 v[124:127], v[146:149], v[178:181], v[124:127]
	v_mfma_f32_16x16x32_bf16 v[120:123], v[154:157], v[178:181], v[120:123]
	v_mfma_f32_16x16x32_bf16 v[108:111], v[146:149], v[186:189], v[108:111]
	v_mfma_f32_16x16x32_bf16 v[104:107], v[154:157], v[186:189], v[104:107]
	v_mfma_f32_16x16x32_bf16 v[92:95], v[146:149], v[198:201], v[92:95]
	v_mfma_f32_16x16x32_bf16 v[88:91], v[154:157], v[198:201], v[88:91]
	v_mfma_f32_16x16x32_bf16 v[76:79], v[146:149], v[206:209], v[76:79]
	v_mfma_f32_16x16x32_bf16 v[72:75], v[154:157], v[206:209], v[72:75]
	v_mfma_f32_16x16x32_bf16 v[116:119], v[158:161], v[174:177], v[116:119]
	v_mfma_f32_16x16x32_bf16 v[112:115], v[166:169], v[174:177], v[112:115]
	v_mfma_f32_16x16x32_bf16 v[100:103], v[158:161], v[182:185], v[100:103]
	v_mfma_f32_16x16x32_bf16 v[96:99], v[166:169], v[182:185], v[96:99]
	v_mfma_f32_16x16x32_bf16 v[84:87], v[158:161], v[194:197], v[84:87]
	v_mfma_f32_16x16x32_bf16 v[80:83], v[166:169], v[194:197], v[80:83]
	v_mfma_f32_16x16x32_bf16 v[68:71], v[158:161], v[202:205], v[68:71]
	v_mfma_f32_16x16x32_bf16 v[64:67], v[166:169], v[202:205], v[64:67]
	v_mfma_f32_16x16x32_bf16 v[116:119], v[162:165], v[178:181], v[116:119]
	v_mfma_f32_16x16x32_bf16 v[112:115], v[170:173], v[178:181], v[112:115]
	v_mfma_f32_16x16x32_bf16 v[100:103], v[162:165], v[186:189], v[100:103]
	v_mfma_f32_16x16x32_bf16 v[96:99], v[170:173], v[186:189], v[96:99]
	v_mfma_f32_16x16x32_bf16 v[84:87], v[162:165], v[198:201], v[84:87]
	v_mfma_f32_16x16x32_bf16 v[80:83], v[170:173], v[198:201], v[80:83]
	v_mfma_f32_16x16x32_bf16 v[68:71], v[162:165], v[206:209], v[68:71]
	v_mfma_f32_16x16x32_bf16 v[64:67], v[170:173], v[206:209], v[64:67]
	s_barrier
	s_add_i32 s30, vcc_lo, s33
	v_lshl_add_u64 v[190:191], s[62:63], 0, v[192:193]
	s_mov_b32 m0, s30
	ds_read_b128 v[174:177], v141 offset:16384
	ds_read_b128 v[178:181], v141 offset:17408
	ds_read_b128 v[182:185], v141 offset:18432
	ds_read_b128 v[186:189], v141 offset:19456
	ds_read_b128 v[194:197], v141 offset:20480
	ds_read_b128 v[198:201], v141 offset:21504
	ds_read_b128 v[202:205], v141 offset:22528
	ds_read_b128 v[206:209], v141 offset:23552
	global_load_lds_dwordx4 v[190:191], off
	s_add_i32 m0, s30, 0x2000
	s_add_u32 s30, s62, 0x40000
	v_lshl_add_u64 v[210:211], s[62:63], 0, v[128:129]
	s_addc_u32 s31, s63, 0
	s_add_i32 vcc_lo, vcc_hi, s33
	global_load_lds_dwordx4 v[210:211], off
	v_lshl_add_u64 v[212:213], s[30:31], 0, v[192:193]
	s_mov_b32 m0, vcc_lo
	v_lshl_add_u64 v[214:215], s[68:69], 0, v[128:129]
	global_load_lds_dwordx4 v[212:213], off
	v_lshl_add_u64 v[212:213], s[30:31], 0, v[128:129]
	s_add_i32 m0, vcc_lo, 0x2000
	s_nop 0
	global_load_lds_dwordx4 v[212:213], off
	v_lshl_add_u64 v[212:213], s[68:69], 0, v[192:193]
	s_mov_b32 m0, s9
	s_nop 0
	global_load_lds_dwordx4 v[212:213], off
	s_mov_b32 m0, s29
	s_nop 0
	global_load_lds_dwordx4 v[214:215], off
	s_waitcnt vmcnt(8)
	s_waitcnt lgkmcnt(0)
	s_barrier
; #define G_STAGE(bufoff, gbase, voff) do { _Pragma("unroll") for (int _i = 0; _i < 2; ++_i) \
;     __builtin_amdgcn_global_load_lds((const unsigned*)((const char*)(gbase) + (voff)[_i]), (LAS unsigned*)(lds + (bufoff) + ldsw + _i * 8192), 16, 0, 0); } while (0)
; #define G_LDA(dst, b, h) do { _Pragma("unroll") for (int m = 0; m < 4; ++m) _Pragma("unroll") for (int k = 0; k < 2; ++k) dst[m][k] = *(const LAS bf16x8*)(lds + G_SA(b, h) + aoff + m * 2048 + k * 1024); } while (0)
; #define G_LDB(dst, b, h) do { _Pragma("unroll") for (int n = 0; n < 2; ++n) _Pragma("unroll") for (int k = 0; k < 2; ++k) dst[n][k] = *(const LAS bf16x8*)(lds + G_SB(b, h) + boff + n * 2048 + k * 1024); } while (0)
; #define G_MMA(ai, bj, At, Bt) do { __builtin_amdgcn_s_setprio(1); _Pragma("unroll") for (int m = 0; m < 4; ++m) _Pragma("unroll") for (int n = 0; n < 2; ++n) _Pragma("unroll") for (int k = 0; k < 2; ++k) \
;     acc[ai][bj][m][n] = __builtin_amdgcn_mfma_f32_16x16x32_bf16(Bt[n][k], At[m][k], acc[ai][bj][m][n], 0, 0, 0); __builtin_amdgcn_s_setprio(0); } while (0)
; #define WAIT_V(n) asm volatile("s_waitcnt vmcnt(" #n ")" ::: "memory")
; #define WAIT_L(n) asm volatile("s_waitcnt lgkmcnt(" #n ")" ::: "memory")
; #define BAR __builtin_amdgcn_s_barrier()
; #define SCHED __builtin_amdgcn_sched_barrier(0)
; template <class Epi>
; __device__ __forceinline__ void gemm_phase(const bf16_t* __restrict__ A, int lda, const bf16_t* __restrict__ Bt, int ldb, int K, int nM, int nN, const Epi& epi, LAS unsigned char* lds, int wv) {
;     ...
;             WAIT_V(8); WAIT_L(0); BAR; G_MMA(0, 0, At, B0); G_MMA(0, 1, At, B1); BAR; SCHED;
;             G_LDA(At, 0, 1); G_STAGE(G_SB(0, 0), b2, voffA); G_STAGE(G_SB(0, 1), b2 + hstep, voffA); G_STAGE(G_SA(0, 0), a2, voffA);
;             WAIT_V(8); WAIT_L(0); BAR; G_MMA(1, 0, At, B0); G_MMA(1, 1, At, B1); BAR; SCHED;
;             G_LDB(B0, 1, 0); G_LDB(B1, 1, 1); SCHED; G_LDA(At, 1, 0); G_STAGE(G_SA(0, 1), a2 + hstep, voffA);
;             WAIT_V(8); WAIT_L(0); BAR; G_MMA(0, 0, At, B0); G_MMA(0, 1, At, B1); BAR; SCHED;
	s_waitcnt lgkmcnt(0)
	v_mfma_f32_16x16x32_bf16 v[60:63], v[142:145], v[174:177], v[60:63]
	v_mfma_f32_16x16x32_bf16 v[56:59], v[150:153], v[174:177], v[56:59]
	v_mfma_f32_16x16x32_bf16 v[44:47], v[142:145], v[182:185], v[44:47]
	v_mfma_f32_16x16x32_bf16 v[40:43], v[150:153], v[182:185], v[40:43]
	v_mfma_f32_16x16x32_bf16 v[28:31], v[142:145], v[194:197], v[28:31]
	v_mfma_f32_16x16x32_bf16 v[24:27], v[150:153], v[194:197], v[24:27]
	v_mfma_f32_16x16x32_bf16 v[12:15], v[142:145], v[202:205], v[12:15]
	v_mfma_f32_16x16x32_bf16 v[8:11], v[150:153], v[202:205], v[8:11]
	v_mfma_f32_16x16x32_bf16 v[60:63], v[146:149], v[178:181], v[60:63]
	v_mfma_f32_16x16x32_bf16 v[56:59], v[154:157], v[178:181], v[56:59]
	v_mfma_f32_16x16x32_bf16 v[44:47], v[146:149], v[186:189], v[44:47]
	v_mfma_f32_16x16x32_bf16 v[40:43], v[154:157], v[186:189], v[40:43]
	v_mfma_f32_16x16x32_bf16 v[28:31], v[146:149], v[198:201], v[28:31]
	v_mfma_f32_16x16x32_bf16 v[24:27], v[154:157], v[198:201], v[24:27]
	v_mfma_f32_16x16x32_bf16 v[12:15], v[146:149], v[206:209], v[12:15]
	v_mfma_f32_16x16x32_bf16 v[8:11], v[154:157], v[206:209], v[8:11]
	v_mfma_f32_16x16x32_bf16 v[52:55], v[158:161], v[174:177], v[52:55]
	v_mfma_f32_16x16x32_bf16 v[48:51], v[166:169], v[174:177], v[48:51]
	v_mfma_f32_16x16x32_bf16 v[36:39], v[158:161], v[182:185], v[36:39]
	v_mfma_f32_16x16x32_bf16 v[32:35], v[166:169], v[182:185], v[32:35]
	v_mfma_f32_16x16x32_bf16 v[20:23], v[158:161], v[194:197], v[20:23]
	v_mfma_f32_16x16x32_bf16 v[16:19], v[166:169], v[194:197], v[16:19]
	v_mfma_f32_16x16x32_bf16 v[4:7], v[158:161], v[202:205], v[4:7]
	v_mfma_f32_16x16x32_bf16 v[0:3], v[166:169], v[202:205], v[0:3]
	v_mfma_f32_16x16x32_bf16 v[52:55], v[162:165], v[178:181], v[52:55]
	v_mfma_f32_16x16x32_bf16 v[48:51], v[170:173], v[178:181], v[48:51]
	v_mfma_f32_16x16x32_bf16 v[36:39], v[162:165], v[186:189], v[36:39]
	v_mfma_f32_16x16x32_bf16 v[32:35], v[170:173], v[186:189], v[32:35]
	v_mfma_f32_16x16x32_bf16 v[20:23], v[162:165], v[198:201], v[20:23]
	v_mfma_f32_16x16x32_bf16 v[16:19], v[170:173], v[198:201], v[16:19]
	v_mfma_f32_16x16x32_bf16 v[4:7], v[162:165], v[206:209], v[4:7]
	v_mfma_f32_16x16x32_bf16 v[0:3], v[170:173], v[206:209], v[0:3]
	s_barrier
	s_add_i32 vcc_lo, 0, 0x18000
	s_add_i32 vcc_hi, 0, 0x1c000
	v_add_u32_e32 v154, vcc_lo, v140
	v_add_u32_e32 v170, vcc_hi, v140
	ds_read_b128 v[142:145], v154
	ds_read_b128 v[146:149], v154 offset:1024
	ds_read_b128 v[150:153], v154 offset:2048
	ds_read_b128 v[154:157], v154 offset:3072
	ds_read_b128 v[158:161], v170
	ds_read_b128 v[162:165], v170 offset:1024
	ds_read_b128 v[166:169], v170 offset:2048
	ds_read_b128 v[170:173], v170 offset:3072
	s_add_u32 s30, s68, 0x40000
	s_addc_u32 s31, s69, 0
	s_mov_b32 m0, s38
	v_lshl_add_u64 v[216:217], s[30:31], 0, v[192:193]
	ds_read_b128 v[174:177], v141 offset:32768
	ds_read_b128 v[178:181], v141 offset:33792
	ds_read_b128 v[182:185], v141 offset:34816
	ds_read_b128 v[186:189], v141 offset:35840
	ds_read_b128 v[194:197], v141 offset:36864
	ds_read_b128 v[198:201], v141 offset:37888
	ds_read_b128 v[202:205], v141 offset:38912
	ds_read_b128 v[206:209], v141 offset:39936
	global_load_lds_dwordx4 v[216:217], off
	v_lshl_add_u64 v[216:217], s[30:31], 0, v[128:129]
	s_mov_b32 m0, s39
	s_nop 0
	global_load_lds_dwordx4 v[216:217], off
	s_waitcnt vmcnt(8)
	s_waitcnt lgkmcnt(0)
	s_barrier
	s_waitcnt lgkmcnt(0)
	v_mfma_f32_16x16x32_bf16 v[124:127], v[142:145], v[174:177], v[124:127]
	v_mfma_f32_16x16x32_bf16 v[120:123], v[150:153], v[174:177], v[120:123]
	v_mfma_f32_16x16x32_bf16 v[108:111], v[142:145], v[182:185], v[108:111]
	v_mfma_f32_16x16x32_bf16 v[104:107], v[150:153], v[182:185], v[104:107]
	v_mfma_f32_16x16x32_bf16 v[92:95], v[142:145], v[194:197], v[92:95]
	v_mfma_f32_16x16x32_bf16 v[88:91], v[150:153], v[194:197], v[88:91]
	v_mfma_f32_16x16x32_bf16 v[76:79], v[142:145], v[202:205], v[76:79]
	v_mfma_f32_16x16x32_bf16 v[72:75], v[150:153], v[202:205], v[72:75]
	v_mfma_f32_16x16x32_bf16 v[124:127], v[146:149], v[178:181], v[124:127]
	v_mfma_f32_16x16x32_bf16 v[120:123], v[154:157], v[178:181], v[120:123]
	v_mfma_f32_16x16x32_bf16 v[108:111], v[146:149], v[186:189], v[108:111]
	v_mfma_f32_16x16x32_bf16 v[104:107], v[154:157], v[186:189], v[104:107]
	v_mfma_f32_16x16x32_bf16 v[92:95], v[146:149], v[198:201], v[92:95]
	v_mfma_f32_16x16x32_bf16 v[88:91], v[154:157], v[198:201], v[88:91]
	v_mfma_f32_16x16x32_bf16 v[76:79], v[146:149], v[206:209], v[76:79]
	v_mfma_f32_16x16x32_bf16 v[72:75], v[154:157], v[206:209], v[72:75]
	v_mfma_f32_16x16x32_bf16 v[116:119], v[158:161], v[174:177], v[116:119]
	v_mfma_f32_16x16x32_bf16 v[112:115], v[166:169], v[174:177], v[112:115]
	v_mfma_f32_16x16x32_bf16 v[100:103], v[158:161], v[182:185], v[100:103]
	v_mfma_f32_16x16x32_bf16 v[96:99], v[166:169], v[182:185], v[96:99]
	v_mfma_f32_16x16x32_bf16 v[84:87], v[158:161], v[194:197], v[84:87]
	v_mfma_f32_16x16x32_bf16 v[80:83], v[166:169], v[194:197], v[80:83]
	v_mfma_f32_16x16x32_bf16 v[68:71], v[158:161], v[202:205], v[68:71]
	v_mfma_f32_16x16x32_bf16 v[64:67], v[166:169], v[202:205], v[64:67]
	v_mfma_f32_16x16x32_bf16 v[116:119], v[162:165], v[178:181], v[116:119]
	v_mfma_f32_16x16x32_bf16 v[112:115], v[170:173], v[178:181], v[112:115]
	v_mfma_f32_16x16x32_bf16 v[100:103], v[162:165], v[186:189], v[100:103]
	v_mfma_f32_16x16x32_bf16 v[96:99], v[170:173], v[186:189], v[96:99]
	v_mfma_f32_16x16x32_bf16 v[84:87], v[162:165], v[198:201], v[84:87]
	v_mfma_f32_16x16x32_bf16 v[80:83], v[170:173], v[198:201], v[80:83]
	v_mfma_f32_16x16x32_bf16 v[68:71], v[162:165], v[206:209], v[68:71]
	v_mfma_f32_16x16x32_bf16 v[64:67], v[170:173], v[206:209], v[64:67]
	s_barrier
; __device__ __forceinline__ unsigned cvt_pk_bf16(float lo, float hi) { unsigned r; asm volatile("v_cvt_pk_bf16_f32 %0, %1, %2" : "=v"(r) : "v"(lo), "v"(hi)); return r; }
; __device__ __forceinline__ float sigmoidf_(float x) { return __builtin_amdgcn_rcpf(1.0f + __builtin_amdgcn_exp2f(-1.44269504088896f * x)); }
; #define G_STAGE(bufoff, gbase, voff) do { _Pragma("unroll") for (int _i = 0; _i < 2; ++_i) \
;     __builtin_amdgcn_global_load_lds((const unsigned*)((const char*)(gbase) + (voff)[_i]), (LAS unsigned*)(lds + (bufoff) + ldsw + _i * 8192), 16, 0, 0); } while (0)
; #define G_LDA(dst, b, h) do { _Pragma("unroll") for (int m = 0; m < 4; ++m) _Pragma("unroll") for (int k = 0; k < 2; ++k) dst[m][k] = *(const LAS bf16x8*)(lds + G_SA(b, h) + aoff + m * 2048 + k * 1024); } while (0)
; #define WAIT_V(n) asm volatile("s_waitcnt vmcnt(" #n ")" ::: "memory")
; #define WAIT_L(n) asm volatile("s_waitcnt lgkmcnt(" #n ")" ::: "memory")
; #define BAR __builtin_amdgcn_s_barrier()
; #define SCHED __builtin_amdgcn_sched_barrier(0)
; template <class Epi>
; __device__ __forceinline__ void gemm_phase(const bf16_t* __restrict__ A, int lda, const bf16_t* __restrict__ Bt, int ldb, int K, int nM, int nN, const Epi& epi, LAS unsigned char* lds, int wv) {
;     ...
;             WAIT_V(8); WAIT_L(0); BAR; G_MMA(0, 0, At, B0); G_MMA(0, 1, At, B1); BAR; SCHED;
;             G_LDA(At, 1, 1); G_STAGE(G_SB(1, 0), b3, voffA); G_STAGE(G_SB(1, 1), b3 + hstep, voffA); G_STAGE(G_SA(1, 0), a3, voffA);
;             WAIT_V(8); WAIT_L(0); BAR; G_MMA(1, 0, At, B0); G_MMA(1, 1, At, B1); BAR; SCHED;
;         }
;     __device__ __forceinline__ void operator()(AccRef acc, int pm, int pn, int wr, int wc, int fr, int fq) const {
;     ...
;             for (int m = 0; m < 4; ++m) { bf16_t* rp = act + (size_t)EPI_ROW(ai, m) * DFF + pn * 128 + wc * 32 + 8 * fq;
;                 float r[2][4];
; #pragma unroll
;                 for (int n = 0; n < 2; ++n) { const f32x4 g = acc[ai][0][m][n], u = acc[ai][1][m][n];
; #pragma unroll
;                     for (int j = 0; j < 4; ++j) r[n][j] = g[j] * sigmoidf_(g[j]) * u[j]; }
;                 u32x4 w; w.x = cvt_pk_bf16(r[0][0], r[0][1]); w.y = cvt_pk_bf16(r[0][2], r[0][3]); w.z = cvt_pk_bf16(r[1][0], r[1][1]); w.w = cvt_pk_bf16(r[1][2], r[1][3]);
;                 *(u32x4*)rp = w; }
	s_add_i32 s30, vcc_lo, s33
	v_lshl_add_u64 v[190:191], v[190:191], 0, s[10:11]
	s_mov_b32 m0, s30
	ds_read_b128 v[174:177], v141 offset:49152
	ds_read_b128 v[178:181], v141 offset:50176
	ds_read_b128 v[182:185], v141 offset:51200
	ds_read_b128 v[186:189], v141 offset:52224
	ds_read_b128 v[194:197], v141 offset:53248
	ds_read_b128 v[198:201], v141 offset:54272
	ds_read_b128 v[202:205], v141 offset:55296
	ds_read_b128 v[206:209], v141 offset:56320
	global_load_lds_dwordx4 v[190:191], off
	s_add_i32 m0, s30, 0x2000
	s_add_u32 s30, s62, 0x40080
	v_lshl_add_u64 v[190:191], v[210:211], 0, s[10:11]
	s_addc_u32 s31, s63, 0
	s_add_i32 s62, vcc_hi, s33
	global_load_lds_dwordx4 v[190:191], off
	v_lshl_add_u64 v[190:191], s[30:31], 0, v[192:193]
	s_mov_b32 m0, s62
	s_nop 0
	global_load_lds_dwordx4 v[190:191], off
	v_lshl_add_u64 v[190:191], s[30:31], 0, v[128:129]
	s_add_i32 m0, s62, 0x2000
	s_nop 0
	global_load_lds_dwordx4 v[190:191], off
	v_lshl_add_u64 v[190:191], v[212:213], 0, s[10:11]
	s_mov_b32 m0, s71
	s_nop 0
	global_load_lds_dwordx4 v[190:191], off
	v_lshl_add_u64 v[190:191], v[214:215], 0, s[10:11]
	s_mov_b32 m0, s72
	s_nop 0
	global_load_lds_dwordx4 v[190:191], off
	s_waitcnt vmcnt(8)
	s_waitcnt lgkmcnt(0)
	s_barrier
	s_waitcnt lgkmcnt(0)
	v_mfma_f32_16x16x32_bf16 v[60:63], v[142:145], v[174:177], v[60:63]
	v_mfma_f32_16x16x32_bf16 v[56:59], v[150:153], v[174:177], v[56:59]
	v_mfma_f32_16x16x32_bf16 v[44:47], v[142:145], v[182:185], v[44:47]
	v_mfma_f32_16x16x32_bf16 v[40:43], v[150:153], v[182:185], v[40:43]
	v_mfma_f32_16x16x32_bf16 v[28:31], v[142:145], v[194:197], v[28:31]
	v_mfma_f32_16x16x32_bf16 v[24:27], v[150:153], v[194:197], v[24:27]
	v_mfma_f32_16x16x32_bf16 v[12:15], v[142:145], v[202:205], v[12:15]
	v_mfma_f32_16x16x32_bf16 v[8:11], v[150:153], v[202:205], v[8:11]
	v_mfma_f32_16x16x32_bf16 v[60:63], v[146:149], v[178:181], v[60:63]
	v_mfma_f32_16x16x32_bf16 v[56:59], v[154:157], v[178:181], v[56:59]
	v_mfma_f32_16x16x32_bf16 v[44:47], v[146:149], v[186:189], v[44:47]
	v_mfma_f32_16x16x32_bf16 v[40:43], v[154:157], v[186:189], v[40:43]
	v_mfma_f32_16x16x32_bf16 v[28:31], v[146:149], v[198:201], v[28:31]
	v_mfma_f32_16x16x32_bf16 v[24:27], v[154:157], v[198:201], v[24:27]
	v_mfma_f32_16x16x32_bf16 v[12:15], v[146:149], v[206:209], v[12:15]
	v_mfma_f32_16x16x32_bf16 v[8:11], v[154:157], v[206:209], v[8:11]
	v_mfma_f32_16x16x32_bf16 v[52:55], v[158:161], v[174:177], v[52:55]
	v_mfma_f32_16x16x32_bf16 v[48:51], v[166:169], v[174:177], v[48:51]
	v_mfma_f32_16x16x32_bf16 v[36:39], v[158:161], v[182:185], v[36:39]
	v_mfma_f32_16x16x32_bf16 v[32:35], v[166:169], v[182:185], v[32:35]
	v_mfma_f32_16x16x32_bf16 v[20:23], v[158:161], v[194:197], v[20:23]
	v_mfma_f32_16x16x32_bf16 v[16:19], v[166:169], v[194:197], v[16:19]
	v_mfma_f32_16x16x32_bf16 v[4:7], v[158:161], v[202:205], v[4:7]
	v_mfma_f32_16x16x32_bf16 v[0:3], v[166:169], v[202:205], v[0:3]
	v_mfma_f32_16x16x32_bf16 v[52:55], v[162:165], v[178:181], v[52:55]
	v_mfma_f32_16x16x32_bf16 v[48:51], v[170:173], v[178:181], v[48:51]
	v_mfma_f32_16x16x32_bf16 v[36:39], v[162:165], v[186:189], v[36:39]
	v_mfma_f32_16x16x32_bf16 v[32:35], v[170:173], v[186:189], v[32:35]
	v_mfma_f32_16x16x32_bf16 v[20:23], v[162:165], v[198:201], v[20:23]
	v_mfma_f32_16x16x32_bf16 v[16:19], v[170:173], v[198:201], v[16:19]
	v_mfma_f32_16x16x32_bf16 v[4:7], v[162:165], v[206:209], v[4:7]
	v_mfma_f32_16x16x32_bf16 v[0:3], v[170:173], v[206:209], v[0:3]
	s_barrier
	s_add_i32 s95, s95, 2
	s_add_u32 s60, s60, 0x100
	s_addc_u32 s61, s61, 0
	s_cmp_gt_u32 s95, 13
	s_cbranch_scc0 .LBB0_28
	v_mul_f32_e32 v137, 0xbfb8aa3b, v124
	v_exp_f32_e32 v137, v137
	v_mul_f32_e32 v146, 0xbfb8aa3b, v125
	v_exp_f32_e32 v146, v146
	v_mov_b32_e32 v134, v139
	v_add_f32_e32 v137, 1.0, v137
	v_rcp_f32_e32 v137, v137
	v_add_f32_e32 v146, 1.0, v146
	v_rcp_f32_e32 v146, v146
	v_mov_b32_e32 v135, v138
	v_mul_f32_e32 v124, v124, v137
	v_mul_f32_e32 v116, v124, v116
	v_mul_f32_e32 v124, v125, v146
	v_mul_f32_e32 v125, 0xbfb8aa3b, v126
	v_exp_f32_e32 v125, v125
	v_mul_f32_e32 v137, 0xbfb8aa3b, v127
	v_exp_f32_e32 v137, v137
	v_mul_f32_e32 v117, v124, v117
	v_add_f32_e32 v124, 1.0, v125
	v_rcp_f32_e32 v124, v124
	v_add_f32_e32 v125, 1.0, v137
	v_mul_f32_e32 v137, 0xbfb8aa3b, v120
	v_rcp_f32_e32 v125, v125
	v_exp_f32_e32 v137, v137
	v_mul_f32_e32 v124, v126, v124
	v_mul_f32_e32 v124, v124, v118
	v_mul_f32_e32 v118, v127, v125
	v_add_f32_e32 v125, 1.0, v137
	v_rcp_f32_e32 v125, v125
	v_mul_f32_e32 v126, 0xbfb8aa3b, v121
	v_mul_f32_e32 v127, v118, v119
	v_exp_f32_e32 v126, v126
	v_mul_f32_e32 v118, v120, v125
	v_mul_f32_e32 v120, v118, v112
	v_mul_f32_e32 v118, 0xbfb8aa3b, v122
	v_exp_f32_e32 v118, v118
	v_mul_f32_e32 v119, 0xbfb8aa3b, v123
	v_exp_f32_e32 v119, v119
	v_add_f32_e32 v112, 1.0, v126
	v_rcp_f32_e32 v112, v112
	v_add_f32_e32 v118, 1.0, v118
	s_lshl_b32 s30, s58, 8
	v_readlane_b32 s31, v253, 5
	v_rcp_f32_e32 v118, v118
	v_add_f32_e32 v119, 1.0, v119
	s_add_i32 s30, s30, s31
	v_rcp_f32_e32 v119, v119
	v_add_u32_e32 v136, s30, v135
	s_lshl_b32 s30, s7, 7
	v_lshlrev_b32_e32 v142, 3, v134
	v_mov_b64_e32 v[134:135], s[20:21]
	s_movk_i32 s46, 0x1600
	s_ashr_i32 s31, s30, 31
	v_mad_i64_i32 v[144:145], s[58:59], v136, s46, v[134:135]
	v_mul_f32_e32 v112, v121, v112
	s_lshl_b64 s[58:59], s[30:31], 1
	v_mul_f32_e32 v121, v112, v113
	v_mul_f32_e32 v112, v122, v118
	v_ashrrev_i32_e32 v143, 31, v142
	v_lshl_add_u64 v[144:145], v[144:145], 0, s[58:59]
	s_mov_b32 s7, s5
	v_mul_f32_e32 v122, v112, v114
	v_mul_f32_e32 v112, v123, v119
	v_lshl_add_u64 v[144:145], v[144:145], 0, s[6:7]
	v_mul_f32_e32 v123, v112, v115
	v_lshlrev_b64 v[112:113], 1, v[142:143]
; __device__ __forceinline__ unsigned cvt_pk_bf16(float lo, float hi) { unsigned r; asm volatile("v_cvt_pk_bf16_f32 %0, %1, %2" : "=v"(r) : "v"(lo), "v"(hi)); return r; }
; __device__ __forceinline__ float sigmoidf_(float x) { return __builtin_amdgcn_rcpf(1.0f + __builtin_amdgcn_exp2f(-1.44269504088896f * x)); }
;     __device__ __forceinline__ void operator()(AccRef acc, int pm, int pn, int wr, int wc, int fr, int fq) const {
;     ...
;             for (int m = 0; m < 4; ++m) { bf16_t* rp = act + (size_t)EPI_ROW(ai, m) * DFF + pn * 128 + wc * 32 + 8 * fq;
;                 float r[2][4];
; #pragma unroll
;                 for (int n = 0; n < 2; ++n) { const f32x4 g = acc[ai][0][m][n], u = acc[ai][1][m][n];
; #pragma unroll
;                     for (int j = 0; j < 4; ++j) r[n][j] = g[j] * sigmoidf_(g[j]) * u[j]; }
;                 u32x4 w; w.x = cvt_pk_bf16(r[0][0], r[0][1]); w.y = cvt_pk_bf16(r[0][2], r[0][3]); w.z = cvt_pk_bf16(r[1][0], r[1][1]); w.w = cvt_pk_bf16(r[1][2], r[1][3]);
;                 *(u32x4*)rp = w; }
	v_lshl_add_u64 v[118:119], v[144:145], 0, v[112:113]
	v_cvt_pk_bf16_f32 v114, v116, v117
	v_cvt_pk_bf16_f32 v115, v124, v127
	v_cvt_pk_bf16_f32 v116, v120, v121
	v_cvt_pk_bf16_f32 v117, v122, v123
	flat_store_dwordx4 v[118:119], v[114:117]
	s_movk_i32 s67, 0x1600
	s_and_b64 vcc, exec, s[44:45]
	v_mul_f32_e32 v116, 0xbfb8aa3b, v108
	v_exp_f32_e32 v116, v116
	v_mul_f32_e32 v117, 0xbfb8aa3b, v109
	v_exp_f32_e32 v117, v117
	v_add_u32_e32 v114, 16, v136
	v_add_f32_e32 v116, 1.0, v116
	v_rcp_f32_e32 v116, v116
	v_add_f32_e32 v117, 1.0, v117
	v_rcp_f32_e32 v117, v117
	v_mad_i64_i32 v[114:115], s[30:31], v114, s46, v[134:135]
	v_mul_f32_e32 v108, v108, v116
	v_mul_f32_e32 v108, v108, v100
	v_mul_f32_e32 v100, v109, v117
	v_mul_f32_e32 v109, 0xbfb8aa3b, v110
	v_exp_f32_e32 v109, v109
	v_mul_f32_e32 v116, 0xbfb8aa3b, v111
	v_exp_f32_e32 v116, v116
	v_mul_f32_e32 v117, v100, v101
	v_add_f32_e32 v100, 1.0, v109
	v_rcp_f32_e32 v100, v100
	v_add_f32_e32 v101, 1.0, v116
	v_mul_f32_e32 v109, 0xbfb8aa3b, v104
	v_rcp_f32_e32 v101, v101
	v_exp_f32_e32 v109, v109
	v_mul_f32_e32 v100, v110, v100
	v_mul_f32_e32 v102, v100, v102
	v_mul_f32_e32 v100, v111, v101
	v_add_f32_e32 v101, 1.0, v109
	v_rcp_f32_e32 v101, v101
	v_mul_f32_e32 v109, 0xbfb8aa3b, v105
	v_mul_f32_e32 v103, v100, v103
	v_exp_f32_e32 v109, v109
	v_mul_f32_e32 v100, v104, v101
	v_mul_f32_e32 v104, v100, v96
	v_mul_f32_e32 v100, 0xbfb8aa3b, v106
	v_exp_f32_e32 v100, v100
	v_mul_f32_e32 v101, 0xbfb8aa3b, v107
	v_exp_f32_e32 v101, v101
	v_add_f32_e32 v96, 1.0, v109
	v_rcp_f32_e32 v96, v96
	v_add_f32_e32 v100, 1.0, v100
	v_rcp_f32_e32 v100, v100
	v_add_f32_e32 v101, 1.0, v101
	v_rcp_f32_e32 v101, v101
	v_mul_f32_e32 v96, v105, v96
	v_lshl_add_u64 v[114:115], v[114:115], 0, s[58:59]
	v_mul_f32_e32 v105, v96, v97
	v_mul_f32_e32 v96, v106, v100
	v_lshl_add_u64 v[114:115], v[114:115], 0, s[6:7]
	v_mul_f32_e32 v106, v96, v98
	v_mul_f32_e32 v96, v107, v101
	v_mul_f32_e32 v99, v96, v99
	v_lshl_add_u64 v[100:101], v[114:115], 0, v[112:113]
	v_cvt_pk_bf16_f32 v96, v108, v117
	v_cvt_pk_bf16_f32 v97, v102, v103
	v_cvt_pk_bf16_f32 v98, v104, v105
	v_cvt_pk_bf16_f32 v99, v106, v99
	flat_store_dwordx4 v[100:101], v[96:99]
	s_mov_b64 s[62:63], s[56:57]
	s_mov_b64 s[60:61], s[54:55]
	v_mul_f32_e32 v98, 0xbfb8aa3b, v92
	v_exp_f32_e32 v98, v98
	v_mul_f32_e32 v99, 0xbfb8aa3b, v93
	v_exp_f32_e32 v99, v99
	v_add_u32_e32 v96, 32, v136
	v_add_f32_e32 v98, 1.0, v98
	v_rcp_f32_e32 v98, v98
	v_add_f32_e32 v99, 1.0, v99
	v_rcp_f32_e32 v99, v99
	v_mad_i64_i32 v[96:97], s[30:31], v96, s46, v[134:135]
	v_mul_f32_e32 v92, v92, v98
	v_mul_f32_e32 v92, v92, v84
	v_mul_f32_e32 v84, v93, v99
	v_mul_f32_e32 v93, 0xbfb8aa3b, v94
	v_exp_f32_e32 v93, v93
	v_mul_f32_e32 v98, 0xbfb8aa3b, v95
	v_exp_f32_e32 v98, v98
	v_mul_f32_e32 v99, v84, v85
	v_add_f32_e32 v84, 1.0, v93
	v_rcp_f32_e32 v84, v84
	v_add_f32_e32 v85, 1.0, v98
	v_mul_f32_e32 v93, 0xbfb8aa3b, v88
	v_rcp_f32_e32 v85, v85
	v_exp_f32_e32 v93, v93
	v_mul_f32_e32 v84, v94, v84
	v_mul_f32_e32 v86, v84, v86
	v_mul_f32_e32 v84, v95, v85
	v_add_f32_e32 v85, 1.0, v93
	v_rcp_f32_e32 v85, v85
	v_mul_f32_e32 v93, 0xbfb8aa3b, v89
	v_mul_f32_e32 v87, v84, v87
	v_exp_f32_e32 v93, v93
	v_mul_f32_e32 v84, v88, v85
	v_mul_f32_e32 v88, v84, v80
	v_mul_f32_e32 v84, 0xbfb8aa3b, v90
	v_exp_f32_e32 v84, v84
	v_mul_f32_e32 v85, 0xbfb8aa3b, v91
	v_exp_f32_e32 v85, v85
	v_add_f32_e32 v80, 1.0, v93
	v_rcp_f32_e32 v80, v80
	v_add_f32_e32 v84, 1.0, v84
	v_rcp_f32_e32 v84, v84
	v_add_f32_e32 v85, 1.0, v85
	v_rcp_f32_e32 v85, v85
	v_mul_f32_e32 v80, v89, v80
	v_lshl_add_u64 v[96:97], v[96:97], 0, s[58:59]
	v_mul_f32_e32 v89, v80, v81
	v_mul_f32_e32 v80, v90, v84
	v_lshl_add_u64 v[96:97], v[96:97], 0, s[6:7]
	v_mul_f32_e32 v90, v80, v82
	v_mul_f32_e32 v80, v91, v85
	v_mul_f32_e32 v83, v80, v83
	v_lshl_add_u64 v[84:85], v[96:97], 0, v[112:113]
	v_cvt_pk_bf16_f32 v80, v92, v99
	v_cvt_pk_bf16_f32 v81, v86, v87
	v_cvt_pk_bf16_f32 v82, v88, v89
	v_cvt_pk_bf16_f32 v83, v90, v83
	flat_store_dwordx4 v[84:85], v[80:83]
	s_nop 1
	v_mul_f32_e32 v82, 0xbfb8aa3b, v76
	v_exp_f32_e32 v82, v82
	v_mul_f32_e32 v83, 0xbfb8aa3b, v77
	v_exp_f32_e32 v83, v83
	v_add_u32_e32 v80, 48, v136
	v_add_f32_e32 v82, 1.0, v82
	v_rcp_f32_e32 v82, v82
	v_add_f32_e32 v83, 1.0, v83
	v_rcp_f32_e32 v83, v83
	v_mad_i64_i32 v[80:81], s[30:31], v80, s46, v[134:135]
	v_mul_f32_e32 v76, v76, v82
	v_mul_f32_e32 v76, v76, v68
	v_mul_f32_e32 v68, v77, v83
	v_mul_f32_e32 v77, 0xbfb8aa3b, v78
	v_exp_f32_e32 v77, v77
	v_mul_f32_e32 v82, 0xbfb8aa3b, v79
	v_exp_f32_e32 v82, v82
	v_mul_f32_e32 v83, v68, v69
	v_add_f32_e32 v68, 1.0, v77
	v_rcp_f32_e32 v68, v68
	v_add_f32_e32 v69, 1.0, v82
	v_mul_f32_e32 v77, 0xbfb8aa3b, v72
	v_rcp_f32_e32 v69, v69
	v_exp_f32_e32 v77, v77
	v_mul_f32_e32 v68, v78, v68
	v_mul_f32_e32 v70, v68, v70
	v_mul_f32_e32 v68, v79, v69
	v_add_f32_e32 v69, 1.0, v77
	v_rcp_f32_e32 v69, v69
	v_mul_f32_e32 v77, 0xbfb8aa3b, v73
	v_mul_f32_e32 v71, v68, v71
	v_exp_f32_e32 v77, v77
	v_mul_f32_e32 v68, v72, v69
	v_mul_f32_e32 v72, v68, v64
	v_mul_f32_e32 v68, 0xbfb8aa3b, v74
	v_exp_f32_e32 v68, v68
	v_mul_f32_e32 v69, 0xbfb8aa3b, v75
	v_exp_f32_e32 v69, v69
	v_add_f32_e32 v64, 1.0, v77
	v_rcp_f32_e32 v64, v64
	v_add_f32_e32 v68, 1.0, v68
	v_rcp_f32_e32 v68, v68
	v_add_f32_e32 v69, 1.0, v69
	v_rcp_f32_e32 v69, v69
	v_mul_f32_e32 v64, v73, v64
	v_lshl_add_u64 v[80:81], v[80:81], 0, s[58:59]
	v_mul_f32_e32 v73, v64, v65
	v_mul_f32_e32 v64, v74, v68
	v_lshl_add_u64 v[80:81], v[80:81], 0, s[6:7]
	v_mul_f32_e32 v74, v64, v66
	v_mul_f32_e32 v64, v75, v69
	v_mul_f32_e32 v67, v64, v67
	v_lshl_add_u64 v[68:69], v[80:81], 0, v[112:113]
	v_cvt_pk_bf16_f32 v64, v76, v83
; __device__ __forceinline__ unsigned cvt_pk_bf16(float lo, float hi) { unsigned r; asm volatile("v_cvt_pk_bf16_f32 %0, %1, %2" : "=v"(r) : "v"(lo), "v"(hi)); return r; }
; __device__ __forceinline__ float sigmoidf_(float x) { return __builtin_amdgcn_rcpf(1.0f + __builtin_amdgcn_exp2f(-1.44269504088896f * x)); }
;     __device__ __forceinline__ void operator()(AccRef acc, int pm, int pn, int wr, int wc, int fr, int fq) const {
;     ...
;             for (int m = 0; m < 4; ++m) { bf16_t* rp = act + (size_t)EPI_ROW(ai, m) * DFF + pn * 128 + wc * 32 + 8 * fq;
;                 float r[2][4];
; #pragma unroll
;                 for (int n = 0; n < 2; ++n) { const f32x4 g = acc[ai][0][m][n], u = acc[ai][1][m][n];
; #pragma unroll
;                     for (int j = 0; j < 4; ++j) r[n][j] = g[j] * sigmoidf_(g[j]) * u[j]; }
;                 u32x4 w; w.x = cvt_pk_bf16(r[0][0], r[0][1]); w.y = cvt_pk_bf16(r[0][2], r[0][3]); w.z = cvt_pk_bf16(r[1][0], r[1][1]); w.w = cvt_pk_bf16(r[1][2], r[1][3]);
;                 *(u32x4*)rp = w; }
	v_cvt_pk_bf16_f32 v65, v70, v71
	v_cvt_pk_bf16_f32 v66, v72, v73
	v_cvt_pk_bf16_f32 v67, v74, v67
	flat_store_dwordx4 v[68:69], v[64:67]
	s_nop 1
	v_mul_f32_e32 v66, 0xbfb8aa3b, v60
	v_exp_f32_e32 v66, v66
	v_mul_f32_e32 v67, 0xbfb8aa3b, v61
	v_exp_f32_e32 v67, v67
	v_add_u32_e32 v64, 0x80, v136
	v_add_f32_e32 v66, 1.0, v66
	v_rcp_f32_e32 v66, v66
	v_add_f32_e32 v67, 1.0, v67
	v_rcp_f32_e32 v67, v67
	v_mad_i64_i32 v[64:65], s[30:31], v64, s46, v[134:135]
	v_mul_f32_e32 v60, v60, v66
	v_mul_f32_e32 v60, v60, v52
	v_mul_f32_e32 v52, v61, v67
	v_mul_f32_e32 v61, 0xbfb8aa3b, v62
	v_exp_f32_e32 v61, v61
	v_mul_f32_e32 v66, 0xbfb8aa3b, v63
	v_exp_f32_e32 v66, v66
	v_mul_f32_e32 v67, v52, v53
	v_add_f32_e32 v52, 1.0, v61
	v_rcp_f32_e32 v52, v52
	v_add_f32_e32 v53, 1.0, v66
	v_mul_f32_e32 v61, 0xbfb8aa3b, v56
	v_rcp_f32_e32 v53, v53
	v_exp_f32_e32 v61, v61
	v_mul_f32_e32 v52, v62, v52
	v_mul_f32_e32 v54, v52, v54
	v_mul_f32_e32 v52, v63, v53
	v_add_f32_e32 v53, 1.0, v61
	v_rcp_f32_e32 v53, v53
	v_mul_f32_e32 v61, 0xbfb8aa3b, v57
	v_mul_f32_e32 v55, v52, v55
	v_exp_f32_e32 v61, v61
	v_mul_f32_e32 v52, v56, v53
	v_mul_f32_e32 v56, v52, v48
	v_mul_f32_e32 v52, 0xbfb8aa3b, v58
	v_exp_f32_e32 v52, v52
	v_mul_f32_e32 v53, 0xbfb8aa3b, v59
	v_exp_f32_e32 v53, v53
	v_add_f32_e32 v48, 1.0, v61
	v_rcp_f32_e32 v48, v48
	v_add_f32_e32 v52, 1.0, v52
	v_rcp_f32_e32 v52, v52
	v_add_f32_e32 v53, 1.0, v53
	v_rcp_f32_e32 v53, v53
	v_mul_f32_e32 v48, v57, v48
	v_lshl_add_u64 v[64:65], v[64:65], 0, s[58:59]
	v_mul_f32_e32 v57, v48, v49
	v_mul_f32_e32 v48, v58, v52
	v_lshl_add_u64 v[64:65], v[64:65], 0, s[6:7]
	v_mul_f32_e32 v58, v48, v50
	v_mul_f32_e32 v48, v59, v53
	v_mul_f32_e32 v51, v48, v51
	v_lshl_add_u64 v[52:53], v[64:65], 0, v[112:113]
	v_cvt_pk_bf16_f32 v48, v60, v67
	v_cvt_pk_bf16_f32 v49, v54, v55
	v_cvt_pk_bf16_f32 v50, v56, v57
	v_cvt_pk_bf16_f32 v51, v58, v51
	flat_store_dwordx4 v[52:53], v[48:51]
	s_nop 1
	v_mul_f32_e32 v50, 0xbfb8aa3b, v44
	v_exp_f32_e32 v50, v50
	v_mul_f32_e32 v51, 0xbfb8aa3b, v45
	v_exp_f32_e32 v51, v51
	v_add_u32_e32 v48, 0x90, v136
	v_add_f32_e32 v50, 1.0, v50
	v_rcp_f32_e32 v50, v50
	v_add_f32_e32 v51, 1.0, v51
	v_rcp_f32_e32 v51, v51
	v_mad_i64_i32 v[48:49], s[30:31], v48, s46, v[134:135]
	v_mul_f32_e32 v44, v44, v50
	v_mul_f32_e32 v44, v44, v36
	v_mul_f32_e32 v36, v45, v51
	v_mul_f32_e32 v45, 0xbfb8aa3b, v46
	v_exp_f32_e32 v45, v45
	v_mul_f32_e32 v50, 0xbfb8aa3b, v47
	v_exp_f32_e32 v50, v50
	v_mul_f32_e32 v51, v36, v37
	v_add_f32_e32 v36, 1.0, v45
	v_rcp_f32_e32 v36, v36
	v_add_f32_e32 v37, 1.0, v50
	v_mul_f32_e32 v45, 0xbfb8aa3b, v40
	v_rcp_f32_e32 v37, v37
	v_exp_f32_e32 v45, v45
	v_mul_f32_e32 v36, v46, v36
	v_mul_f32_e32 v38, v36, v38
	v_mul_f32_e32 v36, v47, v37
	v_add_f32_e32 v37, 1.0, v45
	v_rcp_f32_e32 v37, v37
	v_mul_f32_e32 v45, 0xbfb8aa3b, v41
	v_mul_f32_e32 v39, v36, v39
	v_exp_f32_e32 v45, v45
	v_mul_f32_e32 v36, v40, v37
	v_mul_f32_e32 v40, v36, v32
	v_mul_f32_e32 v36, 0xbfb8aa3b, v42
	v_exp_f32_e32 v36, v36
	v_mul_f32_e32 v37, 0xbfb8aa3b, v43
	v_exp_f32_e32 v37, v37
	v_add_f32_e32 v32, 1.0, v45
	v_rcp_f32_e32 v32, v32
	v_add_f32_e32 v36, 1.0, v36
	v_rcp_f32_e32 v36, v36
	v_add_f32_e32 v37, 1.0, v37
	v_rcp_f32_e32 v37, v37
	v_mul_f32_e32 v32, v41, v32
	v_lshl_add_u64 v[48:49], v[48:49], 0, s[58:59]
	v_mul_f32_e32 v41, v32, v33
	v_mul_f32_e32 v32, v42, v36
	v_lshl_add_u64 v[48:49], v[48:49], 0, s[6:7]
	v_mul_f32_e32 v42, v32, v34
	v_mul_f32_e32 v32, v43, v37
	v_mul_f32_e32 v35, v32, v35
	v_lshl_add_u64 v[36:37], v[48:49], 0, v[112:113]
	v_cvt_pk_bf16_f32 v32, v44, v51
	v_cvt_pk_bf16_f32 v33, v38, v39
	v_cvt_pk_bf16_f32 v34, v40, v41
	v_cvt_pk_bf16_f32 v35, v42, v35
	flat_store_dwordx4 v[36:37], v[32:35]
; __device__ __forceinline__ unsigned cvt_pk_bf16(float lo, float hi) { unsigned r; asm volatile("v_cvt_pk_bf16_f32 %0, %1, %2" : "=v"(r) : "v"(lo), "v"(hi)); return r; }
; __device__ __forceinline__ float sigmoidf_(float x) { return __builtin_amdgcn_rcpf(1.0f + __builtin_amdgcn_exp2f(-1.44269504088896f * x)); }
; #define WAIT_V(n) asm volatile("s_waitcnt vmcnt(" #n ")" ::: "memory")
; #define BAR __builtin_amdgcn_s_barrier()
; template <class Epi>
; __device__ __forceinline__ void gemm_phase(const bf16_t* __restrict__ A, int lda, const bf16_t* __restrict__ Bt, int ldb, int K, int nM, int nN, const Epi& epi, LAS unsigned char* lds, int wv) {
;     ...
;         if (!has_next) break;
; #pragma unroll
;         for (int a = 0; a < 2; ++a)
; #pragma unroll
;             for (int b = 0; b < 2; ++b)
; #pragma unroll
;                 for (int m = 0; m < 4; ++m)
; #pragma unroll
;                     for (int n = 0; n < 2; ++n) acc[a][b][m][n] = (f32x4){0.f, 0.f, 0.f, 0.f};
;         pm = npm; pn = npn; cA = nA; cB = nB;
;     }
;     WAIT_V(0);
;     if (wr == 0) BAR;
;     BAR;
;     __device__ __forceinline__ void operator()(AccRef acc, int pm, int pn, int wr, int wc, int fr, int fq) const {
;     ...
;             for (int m = 0; m < 4; ++m) { bf16_t* rp = act + (size_t)EPI_ROW(ai, m) * DFF + pn * 128 + wc * 32 + 8 * fq;
;                 float r[2][4];
; #pragma unroll
;                 for (int n = 0; n < 2; ++n) { const f32x4 g = acc[ai][0][m][n], u = acc[ai][1][m][n];
; #pragma unroll
;                     for (int j = 0; j < 4; ++j) r[n][j] = g[j] * sigmoidf_(g[j]) * u[j]; }
;                 u32x4 w; w.x = cvt_pk_bf16(r[0][0], r[0][1]); w.y = cvt_pk_bf16(r[0][2], r[0][3]); w.z = cvt_pk_bf16(r[1][0], r[1][1]); w.w = cvt_pk_bf16(r[1][2], r[1][3]);
;                 *(u32x4*)rp = w; }
	s_nop 1
	v_mul_f32_e32 v34, 0xbfb8aa3b, v28
	v_exp_f32_e32 v34, v34
	v_mul_f32_e32 v35, 0xbfb8aa3b, v29
	v_exp_f32_e32 v35, v35
	v_add_u32_e32 v32, 0xa0, v136
	v_add_f32_e32 v34, 1.0, v34
	v_rcp_f32_e32 v34, v34
	v_add_f32_e32 v35, 1.0, v35
	v_rcp_f32_e32 v35, v35
	v_mad_i64_i32 v[32:33], s[30:31], v32, s46, v[134:135]
	v_mul_f32_e32 v28, v28, v34
	v_mul_f32_e32 v28, v28, v20
	v_mul_f32_e32 v20, v29, v35
	v_mul_f32_e32 v29, 0xbfb8aa3b, v30
	v_exp_f32_e32 v29, v29
	v_mul_f32_e32 v34, 0xbfb8aa3b, v31
	v_exp_f32_e32 v34, v34
	v_mul_f32_e32 v35, v20, v21
	v_add_f32_e32 v20, 1.0, v29
	v_rcp_f32_e32 v20, v20
	v_add_f32_e32 v21, 1.0, v34
	v_mul_f32_e32 v29, 0xbfb8aa3b, v24
	v_rcp_f32_e32 v21, v21
	v_exp_f32_e32 v29, v29
	v_mul_f32_e32 v20, v30, v20
	v_mul_f32_e32 v22, v20, v22
	v_mul_f32_e32 v20, v31, v21
	v_add_f32_e32 v21, 1.0, v29
	v_rcp_f32_e32 v21, v21
	v_mul_f32_e32 v29, 0xbfb8aa3b, v25
	v_mul_f32_e32 v23, v20, v23
	v_exp_f32_e32 v29, v29
	v_mul_f32_e32 v20, v24, v21
	v_mul_f32_e32 v24, v20, v16
	v_mul_f32_e32 v20, 0xbfb8aa3b, v26
	v_exp_f32_e32 v20, v20
	v_mul_f32_e32 v21, 0xbfb8aa3b, v27
	v_exp_f32_e32 v21, v21
	v_add_f32_e32 v16, 1.0, v29
	v_rcp_f32_e32 v16, v16
	v_add_f32_e32 v20, 1.0, v20
	v_rcp_f32_e32 v20, v20
	v_add_f32_e32 v21, 1.0, v21
	v_rcp_f32_e32 v21, v21
	v_mul_f32_e32 v16, v25, v16
	v_lshl_add_u64 v[32:33], v[32:33], 0, s[58:59]
	v_mul_f32_e32 v25, v16, v17
	v_mul_f32_e32 v16, v26, v20
	v_lshl_add_u64 v[32:33], v[32:33], 0, s[6:7]
	v_mul_f32_e32 v26, v16, v18
	v_mul_f32_e32 v16, v27, v21
	v_mul_f32_e32 v19, v16, v19
	v_lshl_add_u64 v[20:21], v[32:33], 0, v[112:113]
	v_cvt_pk_bf16_f32 v16, v28, v35
	v_cvt_pk_bf16_f32 v17, v22, v23
	v_cvt_pk_bf16_f32 v18, v24, v25
	v_cvt_pk_bf16_f32 v19, v26, v19
	flat_store_dwordx4 v[20:21], v[16:19]
	s_nop 1
	v_mul_f32_e32 v18, 0xbfb8aa3b, v12
	v_exp_f32_e32 v18, v18
	v_mul_f32_e32 v19, 0xbfb8aa3b, v13
	v_exp_f32_e32 v19, v19
	v_add_u32_e32 v16, 0xb0, v136
	v_add_f32_e32 v18, 1.0, v18
	v_rcp_f32_e32 v18, v18
	v_add_f32_e32 v19, 1.0, v19
	v_rcp_f32_e32 v19, v19
	v_mad_i64_i32 v[16:17], s[30:31], v16, s46, v[134:135]
	v_mul_f32_e32 v12, v12, v18
	v_mul_f32_e32 v12, v12, v4
	v_mul_f32_e32 v4, v13, v19
	v_mul_f32_e32 v13, 0xbfb8aa3b, v14
	v_exp_f32_e32 v13, v13
	v_mul_f32_e32 v18, 0xbfb8aa3b, v15
	v_exp_f32_e32 v18, v18
	v_mul_f32_e32 v19, v4, v5
	v_add_f32_e32 v4, 1.0, v13
	v_rcp_f32_e32 v4, v4
	v_add_f32_e32 v5, 1.0, v18
	v_mul_f32_e32 v13, 0xbfb8aa3b, v8
	v_rcp_f32_e32 v5, v5
	v_exp_f32_e32 v13, v13
	v_mul_f32_e32 v4, v14, v4
	v_mul_f32_e32 v6, v4, v6
	v_mul_f32_e32 v4, v15, v5
	v_add_f32_e32 v5, 1.0, v13
	v_rcp_f32_e32 v5, v5
	v_mul_f32_e32 v13, 0xbfb8aa3b, v9
	v_mul_f32_e32 v7, v4, v7
	v_exp_f32_e32 v13, v13
	v_mul_f32_e32 v4, v8, v5
	v_mul_f32_e32 v8, v4, v0
	v_mul_f32_e32 v4, 0xbfb8aa3b, v10
	v_exp_f32_e32 v4, v4
	v_mul_f32_e32 v5, 0xbfb8aa3b, v11
	v_exp_f32_e32 v5, v5
	v_add_f32_e32 v0, 1.0, v13
	v_rcp_f32_e32 v0, v0
	v_add_f32_e32 v4, 1.0, v4
	v_rcp_f32_e32 v4, v4
	v_add_f32_e32 v5, 1.0, v5
	v_rcp_f32_e32 v5, v5
	v_mul_f32_e32 v0, v9, v0
	v_lshl_add_u64 v[16:17], v[16:17], 0, s[58:59]
	v_mul_f32_e32 v9, v0, v1
	v_mul_f32_e32 v0, v10, v4
	v_lshl_add_u64 v[16:17], v[16:17], 0, s[6:7]
	v_mul_f32_e32 v10, v0, v2
	v_mul_f32_e32 v0, v11, v5
	v_mul_f32_e32 v3, v0, v3
	v_lshl_add_u64 v[4:5], v[16:17], 0, v[112:113]
	s_mov_b32 s58, s50
	s_mov_b32 s7, s52
	v_cvt_pk_bf16_f32 v0, v12, v19
	v_cvt_pk_bf16_f32 v1, v6, v7
	v_cvt_pk_bf16_f32 v2, v8, v9
	v_cvt_pk_bf16_f32 v3, v10, v3
	flat_store_dwordx4 v[4:5], v[0:3]
	s_cbranch_vccz .LBB0_25
	v_readlane_b32 s8, v253, 10
	s_waitcnt vmcnt(0)
	v_readlane_b32 s9, v253, 11
	s_andn2_b64 vcc, exec, s[8:9]
	s_cbranch_vccnz .LBB0_32
	s_barrier
